# v024 + attention: fully-visible key tiles take a copy of the compute block without causal-mask compares/selects
# speedup vs baseline: 1.0159x; 1.0024x over previous
; #define LAS __attribute__((address_space(3)))
; __device__ __forceinline__ void attn_phase(const Params& p, LAS unsigned char* lds, int cidx) {
;     ...
;             if (!wdone && kt * 64 < tpos0 + 31) {
;                 f32x4 st[2][4];
; #pragma unroll
;                 for (int mt = 0; mt < 2; ++mt)
; #pragma unroll
;                     for (int n = 0; n < 4; ++n) st[mt][n] = (f32x4){0.f, 0.f, 0.f, 0.f};
; #pragma unroll
;                 for (int kk = 0; kk < 4; ++kk)
; #pragma unroll
;                     for (int n = 0; n < 4; ++n) {
;                         const bf16x8 kf = *(const LAS bf16x8*)(Kl + (16 * (fr >> 2) + 4 * n + (fr & 3)) * AT_P + 32 * kk + 8 * fq);
;                         st[0][n] = __builtin_amdgcn_mfma_f32_16x16x32_bf16(kf, qf[0][kk], st[0][n], 0, 0, 0);
;                         st[1][n] = __builtin_amdgcn_mfma_f32_16x16x32_bf16(kf, qf[1][kk], st[1][n], 0, 0, 0);
;                     }
.LBB0_674:
	s_xor_b64 s[20:21], s[20:21], -1
	s_mov_b64 s[18:19], -1
	s_waitcnt lgkmcnt(0)
	s_barrier
	s_and_saveexec_b64 s[78:79], s[20:21]
	s_cbranch_execz .LBB0_680
	s_lshl_b32 s20, s33, 6
	s_cmp_ge_i32 s20, s7
	s_mov_b64 s[18:19], 0
	s_cbranch_scc1 .LBB0_679
	s_add_i32 s32, s20, 94
	s_cmp_lt_i32 s32, s7
	s_cbranch_scc0 .Latt_masked
	ds_read_b128 v[218:221], v171
	ds_read_b128 v[222:225], v171 offset:1088
	ds_read_b128 v[226:229], v171 offset:2176
	ds_read_b128 v[230:233], v171 offset:3264
	ds_read_b128 v[236:239], v171 offset:64
	ds_read_b128 v[240:243], v171 offset:1152
	ds_read_b128 v[244:247], v171 offset:2240
	ds_read_b128 v[248:251], v171 offset:3328
	s_waitcnt lgkmcnt(7)
	v_mfma_f32_16x16x32_bf16 v[34:37], v[218:221], v[98:101], 0
	v_mfma_f32_16x16x32_bf16 v[38:41], v[218:221], v[118:121], 0
	ds_read_b128 v[218:221], v171 offset:128
	s_waitcnt lgkmcnt(7)
	v_mfma_f32_16x16x32_bf16 v[42:45], v[222:225], v[98:101], 0
	v_mfma_f32_16x16x32_bf16 v[46:49], v[222:225], v[118:121], 0
	ds_read_b128 v[222:225], v171 offset:1216
	s_waitcnt lgkmcnt(7)
	v_mfma_f32_16x16x32_bf16 v[50:53], v[226:229], v[98:101], 0
	v_mfma_f32_16x16x32_bf16 v[54:57], v[226:229], v[118:121], 0
	ds_read_b128 v[226:229], v171 offset:2304
	s_waitcnt lgkmcnt(7)
	v_mfma_f32_16x16x32_bf16 v[190:193], v[230:233], v[98:101], 0
	v_mfma_f32_16x16x32_bf16 v[206:209], v[230:233], v[118:121], 0
	ds_read_b128 v[230:233], v171 offset:3392
	s_waitcnt lgkmcnt(7)
	v_mfma_f32_16x16x32_bf16 v[34:37], v[236:239], v[102:105], v[34:37]
	v_mfma_f32_16x16x32_bf16 v[38:41], v[236:239], v[122:125], v[38:41]
	ds_read_b128 v[236:239], v171 offset:192
	s_waitcnt lgkmcnt(7)
	v_mfma_f32_16x16x32_bf16 v[42:45], v[240:243], v[102:105], v[42:45]
	v_mfma_f32_16x16x32_bf16 v[46:49], v[240:243], v[122:125], v[46:49]
	ds_read_b128 v[240:243], v171 offset:1280
	s_waitcnt lgkmcnt(7)
	v_mfma_f32_16x16x32_bf16 v[50:53], v[244:247], v[102:105], v[50:53]
	v_mfma_f32_16x16x32_bf16 v[54:57], v[244:247], v[122:125], v[54:57]
	ds_read_b128 v[244:247], v171 offset:2368
	s_waitcnt lgkmcnt(7)
	v_mfma_f32_16x16x32_bf16 v[190:193], v[248:251], v[102:105], v[190:193]
	v_mfma_f32_16x16x32_bf16 v[206:209], v[248:251], v[122:125], v[206:209]
	ds_read_b128 v[248:251], v171 offset:3456
	s_waitcnt lgkmcnt(7)
	v_mfma_f32_16x16x32_bf16 v[34:37], v[218:221], v[106:109], v[34:37]
	v_mfma_f32_16x16x32_bf16 v[38:41], v[218:221], v[126:129], v[38:41]
	s_waitcnt lgkmcnt(6)
	v_mfma_f32_16x16x32_bf16 v[42:45], v[222:225], v[106:109], v[42:45]
	v_mfma_f32_16x16x32_bf16 v[46:49], v[222:225], v[126:129], v[46:49]
	s_waitcnt lgkmcnt(5)
	v_mfma_f32_16x16x32_bf16 v[50:53], v[226:229], v[106:109], v[50:53]
	v_mfma_f32_16x16x32_bf16 v[54:57], v[226:229], v[126:129], v[54:57]
	s_waitcnt lgkmcnt(4)
	v_mfma_f32_16x16x32_bf16 v[190:193], v[230:233], v[106:109], v[190:193]
	v_mfma_f32_16x16x32_bf16 v[206:209], v[230:233], v[126:129], v[206:209]
	s_waitcnt lgkmcnt(3)
	v_mfma_f32_16x16x32_bf16 v[34:37], v[236:239], v[110:113], v[34:37]
	v_mfma_f32_16x16x32_bf16 v[38:41], v[236:239], v[130:133], v[38:41]
	s_waitcnt lgkmcnt(2)
	v_mfma_f32_16x16x32_bf16 v[42:45], v[240:243], v[110:113], v[42:45]
	v_mfma_f32_16x16x32_bf16 v[46:49], v[240:243], v[130:133], v[46:49]
	s_waitcnt lgkmcnt(1)
	v_mfma_f32_16x16x32_bf16 v[50:53], v[244:247], v[110:113], v[50:53]
	v_mfma_f32_16x16x32_bf16 v[54:57], v[244:247], v[130:133], v[54:57]
	s_waitcnt lgkmcnt(0)
	v_mfma_f32_16x16x32_bf16 v[190:193], v[248:251], v[110:113], v[190:193]
	v_mfma_f32_16x16x32_bf16 v[206:209], v[248:251], v[130:133], v[206:209]
	s_nop 6
	v_exp_f32_e64 v62, -|v193|
	v_mov_b32_e32 v60, v193
	v_exp_f32_e64 v63, -|v209|
	v_max_f32_e32 v65, 0, v209
	v_pk_add_f32 v[62:63], v[62:63], 1.0 op_sel_hi:[1,0]
	v_max_f32_e32 v64, 0, v193
	v_log_f32_e32 v62, v62
	v_log_f32_e32 v63, v63
	v_mov_b32_e32 v61, v209
	v_mov_b32_e32 v193, v208
	v_pk_add_f32 v[62:63], v[64:65], v[62:63]
	v_pk_add_f32 v[60:61], v[60:61], v[62:63] neg_lo:[0,1] neg_hi:[0,1]
	v_pk_add_f32 v[64:65], v[62:63], 0 op_sel_hi:[1,0] neg_lo:[1,0] neg_hi:[1,0]
	v_exp_f32_e64 v62, -|v192|
	v_exp_f32_e64 v63, -|v208|
	v_max_f32_e32 v209, 0, v208
	v_pk_add_f32 v[62:63], v[62:63], 1.0 op_sel_hi:[1,0]
	v_max_f32_e32 v208, 0, v192
	v_log_f32_e32 v62, v62
	v_log_f32_e32 v63, v63
	v_pk_add_f32 v[60:61], v[60:61], 0 op_sel_hi:[1,0]
	v_pk_add_f32 v[208:209], v[208:209], v[62:63]
	s_nop 0
	v_pk_add_f32 v[62:63], v[192:193], v[208:209] neg_lo:[0,1] neg_hi:[0,1]
	v_pk_add_f32 v[62:63], v[62:63], v[64:65]
	v_mov_b32_e32 v192, v208
	v_mov_b32_e32 v193, v209
	v_exp_f32_e64 v208, -|v191|
	v_exp_f32_e64 v209, -|v207|
	v_pk_add_f32 v[192:193], v[64:65], v[192:193] neg_lo:[0,1] neg_hi:[0,1]
	v_mov_b32_e32 v64, v191
	v_mov_b32_e32 v65, v207
	v_pk_add_f32 v[208:209], v[208:209], 1.0 op_sel_hi:[1,0]
	v_log_f32_e32 v208, v208
	v_log_f32_e32 v209, v209
	v_max_f32_e32 v211, 0, v207
	v_max_f32_e32 v210, 0, v191
	v_pk_add_f32 v[208:209], v[210:211], v[208:209]
	v_pk_add_f32 v[64:65], v[64:65], v[208:209] neg_lo:[0,1] neg_hi:[0,1]
	v_pk_add_f32 v[64:65], v[64:65], v[192:193]
	v_pk_add_f32 v[192:193], v[192:193], v[208:209] neg_lo:[0,1] neg_hi:[0,1]
	v_exp_f32_e64 v208, -|v190|
	v_exp_f32_e64 v209, -|v206|
	v_mov_b32_e32 v191, v206
	v_max_f32_e32 v207, 0, v206
	v_pk_add_f32 v[208:209], v[208:209], 1.0 op_sel_hi:[1,0]
	v_log_f32_e32 v208, v208
	v_log_f32_e32 v209, v209
	v_max_f32_e32 v206, 0, v190
	v_pk_add_f32 v[206:207], v[206:207], v[208:209]
	v_exp_f32_e64 v208, -|v53|
	v_exp_f32_e64 v209, -|v57|
	v_pk_add_f32 v[190:191], v[190:191], v[206:207] neg_lo:[0,1] neg_hi:[0,1]
	v_pk_add_f32 v[208:209], v[208:209], 1.0 op_sel_hi:[1,0]
	v_pk_add_f32 v[190:191], v[190:191], v[192:193]
; __device__ __forceinline__ void attn_phase(const Params& p, LAS unsigned char* lds, int cidx) {
;     ...
;                     const int s0 = kt * 64 + 16 * fq, tq0 = tpos0 + fr, tq1 = tpos0 + 16 + fr;
;                     f32x2 run = (f32x2){0.f, 0.f};
; #pragma unroll
;     ...
;                         const f32x2 xv = (f32x2){st[0][idx >> 2][idx & 3], st[1][idx >> 2][idx & 3]};
;                         const f32x2 ax = __builtin_elementwise_abs(xv);
;                         f32x2 e; e.x = __builtin_amdgcn_exp2f(-ax.x); e.y = __builtin_amdgcn_exp2f(-ax.y);
;                         const f32x2 e1 = e + 1.0f;
;                         f32x2 lg; lg.x = __builtin_amdgcn_logf(e1.x); lg.y = __builtin_amdgcn_logf(e1.y);
;                         const f32x2 sp = __builtin_elementwise_max(xv, (f32x2){0.f, 0.f}) + lg;
;                         const f32x2 lw = (xv - sp) + run;
;                         st[0][idx >> 2][idx & 3] = lw.x; st[1][idx >> 2][idx & 3] = lw.y;
;                         f32x2 dec; dec.x = (s0 + idx) < tq0 ? sp.x : 0.f; dec.y = (s0 + idx) < tq1 ? sp.y : 0.f;
;                         run = run - dec;
;                     }
	v_log_f32_e32 v208, v208
	v_log_f32_e32 v209, v209
	v_pk_add_f32 v[206:207], v[192:193], v[206:207] neg_lo:[0,1] neg_hi:[0,1]
	v_mov_b32_e32 v192, v53
	v_mov_b32_e32 v193, v57
	v_max_f32_e32 v211, 0, v57
	v_max_f32_e32 v210, 0, v53
	v_pk_add_f32 v[208:209], v[210:211], v[208:209]
	v_pk_add_f32 v[192:193], v[192:193], v[208:209] neg_lo:[0,1] neg_hi:[0,1]
	v_pk_add_f32 v[192:193], v[192:193], v[206:207]
	v_pk_add_f32 v[206:207], v[206:207], v[208:209] neg_lo:[0,1] neg_hi:[0,1]
	v_exp_f32_e64 v208, -|v52|
	v_exp_f32_e64 v209, -|v56|
	v_mov_b32_e32 v53, v56
	v_max_f32_e32 v57, 0, v56
	v_pk_add_f32 v[208:209], v[208:209], 1.0 op_sel_hi:[1,0]
	v_log_f32_e32 v208, v208
	v_log_f32_e32 v209, v209
	v_max_f32_e32 v56, 0, v52
	v_pk_add_f32 v[56:57], v[56:57], v[208:209]
	v_exp_f32_e64 v208, -|v51|
	v_exp_f32_e64 v209, -|v55|
	v_pk_add_f32 v[52:53], v[52:53], v[56:57] neg_lo:[0,1] neg_hi:[0,1]
	v_pk_add_f32 v[208:209], v[208:209], 1.0 op_sel_hi:[1,0]
	v_pk_add_f32 v[52:53], v[52:53], v[206:207]
	v_log_f32_e32 v208, v208
	v_log_f32_e32 v209, v209
	v_pk_add_f32 v[206:207], v[206:207], v[56:57] neg_lo:[0,1] neg_hi:[0,1]
	v_mov_b32_e32 v56, v51
	v_mov_b32_e32 v57, v55
	v_max_f32_e32 v211, 0, v55
	v_max_f32_e32 v210, 0, v51
	v_pk_add_f32 v[208:209], v[210:211], v[208:209]
	v_pk_add_f32 v[56:57], v[56:57], v[208:209] neg_lo:[0,1] neg_hi:[0,1]
	v_pk_add_f32 v[56:57], v[56:57], v[206:207]
	v_pk_add_f32 v[206:207], v[206:207], v[208:209] neg_lo:[0,1] neg_hi:[0,1]
	v_exp_f32_e64 v208, -|v50|
	v_exp_f32_e64 v209, -|v54|
	v_mov_b32_e32 v51, v54
	v_max_f32_e32 v55, 0, v54
	v_pk_add_f32 v[208:209], v[208:209], 1.0 op_sel_hi:[1,0]
	v_log_f32_e32 v208, v208
	v_log_f32_e32 v209, v209
	v_max_f32_e32 v54, 0, v50
	v_pk_add_f32 v[54:55], v[54:55], v[208:209]
	v_exp_f32_e64 v208, -|v45|
	v_exp_f32_e64 v209, -|v49|
	v_pk_add_f32 v[50:51], v[50:51], v[54:55] neg_lo:[0,1] neg_hi:[0,1]
	v_pk_add_f32 v[208:209], v[208:209], 1.0 op_sel_hi:[1,0]
	v_pk_add_f32 v[50:51], v[50:51], v[206:207]
	v_log_f32_e32 v208, v208
	v_log_f32_e32 v209, v209
	v_pk_add_f32 v[206:207], v[206:207], v[54:55] neg_lo:[0,1] neg_hi:[0,1]
	v_mov_b32_e32 v54, v45
	v_mov_b32_e32 v55, v49
	v_max_f32_e32 v211, 0, v49
	v_max_f32_e32 v210, 0, v45
	v_pk_add_f32 v[208:209], v[210:211], v[208:209]
	v_pk_add_f32 v[54:55], v[54:55], v[208:209] neg_lo:[0,1] neg_hi:[0,1]
	v_pk_add_f32 v[54:55], v[54:55], v[206:207]
	v_pk_add_f32 v[206:207], v[206:207], v[208:209] neg_lo:[0,1] neg_hi:[0,1]
	v_exp_f32_e64 v208, -|v44|
	v_exp_f32_e64 v209, -|v48|
	v_mov_b32_e32 v45, v48
	v_max_f32_e32 v49, 0, v48
	v_pk_add_f32 v[208:209], v[208:209], 1.0 op_sel_hi:[1,0]
	v_log_f32_e32 v208, v208
	v_log_f32_e32 v209, v209
	v_max_f32_e32 v48, 0, v44
	v_pk_add_f32 v[48:49], v[48:49], v[208:209]
	v_exp_f32_e64 v208, -|v43|
	v_exp_f32_e64 v209, -|v47|
	v_pk_add_f32 v[44:45], v[44:45], v[48:49] neg_lo:[0,1] neg_hi:[0,1]
	v_pk_add_f32 v[208:209], v[208:209], 1.0 op_sel_hi:[1,0]
	v_pk_add_f32 v[44:45], v[44:45], v[206:207]
	v_log_f32_e32 v208, v208
	v_log_f32_e32 v209, v209
	v_pk_add_f32 v[206:207], v[206:207], v[48:49] neg_lo:[0,1] neg_hi:[0,1]
	v_mov_b32_e32 v48, v43
	v_mov_b32_e32 v49, v47
	v_max_f32_e32 v211, 0, v47
	v_max_f32_e32 v210, 0, v43
	v_pk_add_f32 v[208:209], v[210:211], v[208:209]
	v_pk_add_f32 v[48:49], v[48:49], v[208:209] neg_lo:[0,1] neg_hi:[0,1]
	v_pk_add_f32 v[48:49], v[48:49], v[206:207]
	v_pk_add_f32 v[206:207], v[206:207], v[208:209] neg_lo:[0,1] neg_hi:[0,1]
	v_exp_f32_e64 v208, -|v42|
	v_exp_f32_e64 v209, -|v46|
	v_mov_b32_e32 v43, v46
	v_max_f32_e32 v47, 0, v46
	v_pk_add_f32 v[208:209], v[208:209], 1.0 op_sel_hi:[1,0]
	v_log_f32_e32 v208, v208
	v_log_f32_e32 v209, v209
	v_max_f32_e32 v46, 0, v42
	v_pk_add_f32 v[208:209], v[46:47], v[208:209]
	s_nop 0
	v_pk_add_f32 v[42:43], v[42:43], v[208:209] neg_lo:[0,1] neg_hi:[0,1]
	s_nop 0
	v_pk_add_f32 v[46:47], v[42:43], v[206:207]
	s_nop 0
	v_mov_b32_e32 v42, v208
	v_mov_b32_e32 v43, v209
	v_exp_f32_e64 v208, -|v37|
	v_exp_f32_e64 v209, -|v41|
	v_pk_add_f32 v[42:43], v[206:207], v[42:43] neg_lo:[0,1] neg_hi:[0,1]
	v_mov_b32_e32 v206, v37
	v_mov_b32_e32 v207, v41
	v_pk_add_f32 v[208:209], v[208:209], 1.0 op_sel_hi:[1,0]
	v_log_f32_e32 v208, v208
	v_log_f32_e32 v209, v209
	v_max_f32_e32 v211, 0, v41
	v_max_f32_e32 v210, 0, v37
	v_pk_add_f32 v[208:209], v[210:211], v[208:209]
	v_pk_add_f32 v[206:207], v[206:207], v[208:209] neg_lo:[0,1] neg_hi:[0,1]
	v_pk_add_f32 v[206:207], v[206:207], v[42:43]
	v_pk_add_f32 v[42:43], v[42:43], v[208:209] neg_lo:[0,1] neg_hi:[0,1]
	v_exp_f32_e64 v208, -|v36|
	v_exp_f32_e64 v209, -|v40|
	v_mov_b32_e32 v37, v40
	v_max_f32_e32 v41, 0, v40
	v_pk_add_f32 v[208:209], v[208:209], 1.0 op_sel_hi:[1,0]
	v_log_f32_e32 v208, v208
	v_log_f32_e32 v209, v209
	v_max_f32_e32 v40, 0, v36
	v_pk_add_f32 v[40:41], v[40:41], v[208:209]
	v_exp_f32_e64 v208, -|v35|
	v_exp_f32_e64 v209, -|v39|
	v_pk_add_f32 v[36:37], v[36:37], v[40:41] neg_lo:[0,1] neg_hi:[0,1]
	v_pk_add_f32 v[208:209], v[208:209], 1.0 op_sel_hi:[1,0]
	v_pk_add_f32 v[36:37], v[36:37], v[42:43]
	v_log_f32_e32 v208, v208
	v_log_f32_e32 v209, v209
	v_pk_add_f32 v[40:41], v[42:43], v[40:41] neg_lo:[0,1] neg_hi:[0,1]
	v_mov_b32_e32 v42, v35
	v_mov_b32_e32 v43, v39
	v_max_f32_e32 v211, 0, v39
	v_max_f32_e32 v210, 0, v35
	v_pk_add_f32 v[208:209], v[210:211], v[208:209]
	v_pk_add_f32 v[42:43], v[42:43], v[208:209] neg_lo:[0,1] neg_hi:[0,1]
	v_pk_add_f32 v[210:211], v[42:43], v[40:41]
	v_mov_b32_e32 v42, v208
	v_mov_b32_e32 v43, v209
	v_pk_add_f32 v[40:41], v[40:41], v[42:43] neg_lo:[0,1] neg_hi:[0,1]
	v_exp_f32_e64 v42, -|v34|
	v_exp_f32_e64 v43, -|v38|
	v_mov_b32_e32 v35, v38
	v_max_f32_e32 v39, 0, v38
	v_pk_add_f32 v[42:43], v[42:43], 1.0 op_sel_hi:[1,0]
	v_log_f32_e32 v42, v42
	v_log_f32_e32 v43, v43
	v_max_f32_e32 v38, 0, v34
	v_or_b32_e32 v1, v201, v196
	v_lshlrev_b32_e32 v1, 2, v1
	v_pk_add_f32 v[38:39], v[38:39], v[42:43]
	v_xor_b32_e32 v1, 0x80, v1
	v_pk_add_f32 v[34:35], v[34:35], v[38:39] neg_lo:[0,1] neg_hi:[0,1]
	v_pk_add_f32 v[38:39], v[40:41], v[38:39] neg_lo:[0,1] neg_hi:[0,1]
	v_pk_add_f32 v[34:35], v[34:35], v[40:41]
	ds_bpermute_b32 v40, v202, v38
	ds_bpermute_b32 v41, v202, v39
	ds_bpermute_b32 v42, v1, v38
	ds_bpermute_b32 v43, v1, v39
	ds_bpermute_b32 v208, v203, v38
	ds_bpermute_b32 v209, v203, v39
	s_waitcnt lgkmcnt(4)
; #define LAS __attribute__((address_space(3)))
; __device__ __forceinline__ void attn_phase(const Params& p, LAS unsigned char* lds, int cidx) {
;     ...
;                     f32x2 t16, t32, t48;
;                     t16.x = __shfl(run.x, (lane + 16) & 63); t16.y = __shfl(run.y, (lane + 16) & 63);
;                     t32.x = __shfl(run.x, (lane + 32) & 63); t32.y = __shfl(run.y, (lane + 32) & 63);
;                     t48.x = __shfl(run.x, (lane + 48) & 63); t48.y = __shfl(run.y, (lane + 48) & 63);
;                     const f32x2 z2 = (f32x2){0.f, 0.f};
;                     const f32x2 higher = (fq < 3 ? t16 : z2) + (fq < 2 ? t32 : z2) + (fq < 1 ? t48 : z2);
;                     const f32x2 base = (f32x2){C[0], C[1]} + higher;
;                     const f32x2 tot = (run + t16) + (t32 + t48);
;                     C[0] += tot.x; C[1] += tot.y;
;                     float w0[16], w1[16];
; #pragma unroll
;                     for (int idx = 0; idx < 16; ++idx) {
;                         const f32x2 a2 = (f32x2){st[0][idx >> 2][idx & 3], st[1][idx >> 2][idx & 3]} + base;
;                         w0[idx] = (s0 + idx) < tq0 ? __builtin_amdgcn_exp2f(a2.x) : 0.f;
;                         w1[idx] = (s0 + idx) < tq1 ? __builtin_amdgcn_exp2f(a2.y) : 0.f;
;                     }
; #pragma unroll
;                     for (int k2 = 0; k2 < 2; ++k2) {
;                         u32x4 pw; pw.x = cvt_pk_bf16(w0[8 * k2 + 0], w0[8 * k2 + 1]); pw.y = cvt_pk_bf16(w0[8 * k2 + 2], w0[8 * k2 + 3]); pw.z = cvt_pk_bf16(w0[8 * k2 + 4], w0[8 * k2 + 5]); pw.w = cvt_pk_bf16(w0[8 * k2 + 6], w0[8 * k2 + 7]);
;                         pb[0][k2] = __builtin_bit_cast(bf16x8, pw);
;                         u32x4 pv; pv.x = cvt_pk_bf16(w1[8 * k2 + 0], w1[8 * k2 + 1]); pv.y = cvt_pk_bf16(w1[8 * k2 + 2], w1[8 * k2 + 3]); pv.z = cvt_pk_bf16(w1[8 * k2 + 4], w1[8 * k2 + 5]); pv.w = cvt_pk_bf16(w1[8 * k2 + 6], w1[8 * k2 + 7]);
;                         pb[1][k2] = __builtin_bit_cast(bf16x8, pv);
;                     }
;                 }
; #pragma unroll
;                 for (int k2 = 0; k2 < 2; ++k2)
; #pragma unroll
;                     for (int dt = 0; dt < 8; ++dt) {
;                         const LAS bf16_t* a0 = Vl + (16 * fq + 8 * k2 + (fr >> 2)) * AT_P + 16 * dt + 4 * (fr & 3);
	v_cndmask_b32_e64 v213, v41, 0, s[8:9]
	v_cndmask_b32_e64 v212, v40, 0, s[8:9]
	s_waitcnt lgkmcnt(2)
	v_cndmask_b32_e64 v215, 0, v43, s[10:11]
	v_cndmask_b32_e64 v214, 0, v42, s[10:11]
	v_pk_add_f32 v[212:213], v[212:213], v[214:215]
	s_waitcnt lgkmcnt(0)
	v_cndmask_b32_e64 v215, 0, v209, s[12:13]
	v_cndmask_b32_e64 v214, 0, v208, s[12:13]
	v_pk_add_f32 v[212:213], v[212:213], v[214:215]
	v_pk_add_f32 v[38:39], v[38:39], v[40:41]
	v_pk_add_f32 v[212:213], v[58:59], v[212:213]
	v_pk_add_f32 v[40:41], v[42:43], v[208:209]
	v_pk_add_f32 v[34:35], v[212:213], v[34:35]
	v_pk_add_f32 v[42:43], v[40:41], v[38:39]
	v_exp_f32_e32 v1, v34
	v_exp_f32_e32 v34, v35
	v_pk_add_f32 v[58:59], v[58:59], v[42:43]
	v_mov_b32_e32 v38, v34
	v_pk_add_f32 v[34:35], v[212:213], v[210:211]
	s_nop 0
	v_exp_f32_e32 v34, v34
	s_nop 0
	v_mov_b32_e32 v39, v34
	v_exp_f32_e32 v34, v35
	s_nop 0
	v_mov_b32_e32 v40, v34
	v_pk_add_f32 v[34:35], v[212:213], v[36:37]
	s_nop 0
	v_exp_f32_e32 v34, v34
	s_nop 0
	v_mov_b32_e32 v36, v34
	v_exp_f32_e32 v34, v35
	s_nop 0
	v_mov_b32_e32 v37, v34
	v_pk_add_f32 v[34:35], v[212:213], v[206:207]
	s_nop 0
	v_exp_f32_e32 v34, v34
	s_nop 0
	v_mov_b32_e32 v41, v34
	v_exp_f32_e32 v34, v35
	s_nop 0
	v_mov_b32_e32 v206, v34
	v_pk_add_f32 v[34:35], v[212:213], v[46:47]
	s_nop 0
	v_exp_f32_e32 v34, v34
	s_nop 0
	v_mov_b32_e32 v46, v34
	v_exp_f32_e32 v34, v35
	s_nop 0
	v_mov_b32_e32 v207, v34
	v_pk_add_f32 v[34:35], v[212:213], v[48:49]
	s_nop 0
	v_exp_f32_e32 v34, v34
	s_nop 0
	v_mov_b32_e32 v47, v34
	v_exp_f32_e32 v34, v35
	s_nop 0
	v_mov_b32_e32 v208, v34
	v_pk_add_f32 v[34:35], v[212:213], v[44:45]
	v_cvt_pk_bf16_f32 v44, v1, v39
	v_cvt_pk_bf16_f32 v45, v36, v41
	v_cvt_pk_bf16_f32 v46, v46, v47
	s_nop 0
	v_exp_f32_e32 v34, v34
	s_nop 0
	v_mov_b32_e32 v48, v34
	v_exp_f32_e32 v34, v35
	s_nop 0
	v_mov_b32_e32 v209, v34
	v_pk_add_f32 v[34:35], v[212:213], v[54:55]
	s_nop 0
	v_exp_f32_e32 v34, v34
	s_nop 0
	v_mov_b32_e32 v49, v34
	v_exp_f32_e32 v34, v35
	v_cvt_pk_bf16_f32 v47, v48, v49
	v_cvt_pk_bf16_f32 v48, v38, v40
	v_cvt_pk_bf16_f32 v49, v37, v206
	s_nop 0
	v_mov_b32_e32 v54, v34
	v_pk_add_f32 v[34:35], v[212:213], v[50:51]
	v_cvt_pk_bf16_f32 v50, v207, v208
	v_cvt_pk_bf16_f32 v51, v209, v54
	s_nop 0
	v_exp_f32_e32 v34, v34
	s_nop 0
	v_mov_b32_e32 v55, v34
	v_exp_f32_e32 v34, v35
	s_nop 0
	v_mov_b32_e32 v210, v34
	v_pk_add_f32 v[34:35], v[212:213], v[56:57]
	s_nop 0
	v_exp_f32_e32 v34, v34
	s_nop 0
	v_mov_b32_e32 v56, v34
	v_exp_f32_e32 v34, v35
	v_cvt_pk_bf16_f32 v38, v55, v56
	s_nop 0
	v_mov_b32_e32 v57, v34
	v_pk_add_f32 v[34:35], v[212:213], v[52:53]
	s_nop 0
	v_exp_f32_e32 v34, v34
	s_nop 0
	v_mov_b32_e32 v52, v34
	v_exp_f32_e32 v34, v35
	s_nop 0
	v_mov_b32_e32 v53, v34
	v_pk_add_f32 v[34:35], v[212:213], v[192:193]
	s_nop 0
	v_exp_f32_e32 v34, v34
	s_nop 0
	v_mov_b32_e32 v192, v34
	v_exp_f32_e32 v34, v35
	v_cvt_pk_bf16_f32 v39, v52, v192
	s_nop 0
	v_mov_b32_e32 v193, v34
	v_pk_add_f32 v[34:35], v[212:213], v[190:191]
	s_nop 0
	v_exp_f32_e32 v34, v34
	s_nop 0
	v_mov_b32_e32 v190, v34
	v_exp_f32_e32 v34, v35
	s_nop 0
	v_mov_b32_e32 v191, v34
	v_pk_add_f32 v[34:35], v[212:213], v[64:65]
	s_nop 0
	v_exp_f32_e32 v34, v34
	s_nop 0
	v_mov_b32_e32 v64, v34
	v_exp_f32_e32 v34, v35
	v_cvt_pk_bf16_f32 v40, v190, v64
	s_nop 0
	v_mov_b32_e32 v65, v34
	v_pk_add_f32 v[34:35], v[212:213], v[62:63]
	s_nop 0
	v_exp_f32_e32 v34, v34
	s_nop 0
	v_mov_b32_e32 v62, v34
	v_exp_f32_e32 v34, v35
	s_nop 0
	v_mov_b32_e32 v63, v34
	v_pk_add_f32 v[34:35], v[212:213], v[60:61]
	v_readlane_b32 s20, v234, 43
	v_exp_f32_e32 v34, v34
	v_exp_f32_e32 v35, v35
	v_readlane_b32 s21, v234, 44
	v_mov_b32_e32 v60, v35
	v_cvt_pk_bf16_f32 v41, v62, v34
	v_cvt_pk_bf16_f32 v34, v210, v57
	v_cvt_pk_bf16_f32 v35, v53, v193
	v_cvt_pk_bf16_f32 v36, v191, v65
	v_cvt_pk_bf16_f32 v37, v63, v60
	ds_read_b64_tr_b16 v[218:219], v173 offset:17408
	ds_read_b64_tr_b16 v[220:221], v173 offset:18496
	ds_read_b64_tr_b16 v[222:223], v173 offset:17440
	ds_read_b64_tr_b16 v[224:225], v173 offset:18528
	ds_read_b64_tr_b16 v[226:227], v173 offset:17472
	ds_read_b64_tr_b16 v[228:229], v173 offset:18560
	ds_read_b64_tr_b16 v[230:231], v173 offset:17504
	ds_read_b64_tr_b16 v[232:233], v173 offset:18592
	ds_read_b64_tr_b16 v[236:237], v173 offset:17536
	ds_read_b64_tr_b16 v[238:239], v173 offset:18624
	ds_read_b64_tr_b16 v[240:241], v173 offset:17568
	ds_read_b64_tr_b16 v[242:243], v173 offset:18656
	s_mov_b32 s18, 0xc3200000
	v_cmp_gt_f32_e32 vcc, s18, v58
	v_cmp_gt_f32_e64 s[18:19], s18, v59
	s_waitcnt lgkmcnt(10)
	v_mfma_f32_16x16x32_bf16 v[158:161], v[218:221], v[44:47], v[158:161]
	v_mfma_f32_16x16x32_bf16 v[94:97], v[218:221], v[48:51], v[94:97]
	ds_read_b64_tr_b16 v[218:219], v173 offset:17600
	ds_read_b64_tr_b16 v[220:221], v173 offset:18688
	s_and_b64 s[18:19], vcc, s[18:19]
	v_cndmask_b32_e64 v1, 0, 1, s[18:19]
	s_waitcnt lgkmcnt(10)
	v_mfma_f32_16x16x32_bf16 v[154:157], v[222:225], v[44:47], v[154:157]
	v_mfma_f32_16x16x32_bf16 v[90:93], v[222:225], v[48:51], v[90:93]
	ds_read_b64_tr_b16 v[222:223], v173 offset:17632
	ds_read_b64_tr_b16 v[224:225], v173 offset:18720
	v_cmp_ne_u32_e32 vcc, 0, v1
	s_cmp_eq_u64 vcc, -1
	s_cselect_b64 s[18:19], -1, 0
	s_waitcnt lgkmcnt(10)
	v_mfma_f32_16x16x32_bf16 v[150:153], v[226:229], v[44:47], v[150:153]
	v_mfma_f32_16x16x32_bf16 v[86:89], v[226:229], v[48:51], v[86:89]
	ds_read_b64_tr_b16 v[226:227], v173 offset:19584
	ds_read_b64_tr_b16 v[228:229], v173 offset:20672
	s_and_b64 s[22:23], s[20:21], s[18:19]
	s_waitcnt lgkmcnt(10)
	v_mfma_f32_16x16x32_bf16 v[146:149], v[230:233], v[44:47], v[146:149]
	v_mfma_f32_16x16x32_bf16 v[82:85], v[230:233], v[48:51], v[82:85]
	ds_read_b64_tr_b16 v[230:231], v173 offset:19616
	ds_read_b64_tr_b16 v[232:233], v173 offset:20704
	s_waitcnt lgkmcnt(10)
; #define LAS __attribute__((address_space(3)))
; __device__ __forceinline__ void attn_phase(const Params& p, LAS unsigned char* lds, int cidx) {
;     ...
;                 for (int kk = 0; kk < 4; ++kk)
; #pragma unroll
;                     for (int n = 0; n < 4; ++n) {
;                         const bf16x8 kf = *(const LAS bf16x8*)(Kl + (16 * (fr >> 2) + 4 * n + (fr & 3)) * AT_P + 32 * kk + 8 * fq);
;                         st[0][n] = __builtin_amdgcn_mfma_f32_16x16x32_bf16(kf, qf[0][kk], st[0][n], 0, 0, 0);
;                         st[1][n] = __builtin_amdgcn_mfma_f32_16x16x32_bf16(kf, qf[1][kk], st[1][n], 0, 0, 0);
;                     }
;     ...
; #pragma unroll
;                 for (int k2 = 0; k2 < 2; ++k2)
; #pragma unroll
;                     for (int dt = 0; dt < 8; ++dt) {
;                         const LAS bf16_t* a0 = Vl + (16 * fq + 8 * k2 + (fr >> 2)) * AT_P + 16 * dt + 4 * (fr & 3);
;                         const s16x4 lo = __builtin_amdgcn_ds_read_tr16_b64_v4i16((LAS s16x4*)a0), hi = __builtin_amdgcn_ds_read_tr16_b64_v4i16((LAS s16x4*)(a0 + 4 * AT_P));
;                         const bf16x8 vf = (bf16x8){lo[0], lo[1], lo[2], lo[3], hi[0], hi[1], hi[2], hi[3]};
;                         o[0][dt] = __builtin_amdgcn_mfma_f32_16x16x32_bf16(vf, pb[0][k2], o[0][dt], 0, 0, 0);
;                         o[1][dt] = __builtin_amdgcn_mfma_f32_16x16x32_bf16(vf, pb[1][k2], o[1][dt], 0, 0, 0);
;                     }
;                 if (__builtin_amdgcn_ballot_w64(C[0] < -160.f && C[1] < -160.f) == ~0ull) { wdone = true;     if (lane == 0) misc[8 + wid] = 1; }
	v_mfma_f32_16x16x32_bf16 v[142:145], v[236:239], v[44:47], v[142:145]
	v_mfma_f32_16x16x32_bf16 v[78:81], v[236:239], v[48:51], v[78:81]
	ds_read_b64_tr_b16 v[236:237], v173 offset:19648
	ds_read_b64_tr_b16 v[238:239], v173 offset:20736
	s_waitcnt lgkmcnt(10)
	v_mfma_f32_16x16x32_bf16 v[138:141], v[240:243], v[44:47], v[138:141]
	v_mfma_f32_16x16x32_bf16 v[74:77], v[240:243], v[48:51], v[74:77]
	ds_read_b64_tr_b16 v[240:241], v173 offset:19680
	ds_read_b64_tr_b16 v[242:243], v173 offset:20768
	s_waitcnt lgkmcnt(10)
	v_mfma_f32_16x16x32_bf16 v[134:137], v[218:221], v[44:47], v[134:137]
	v_mfma_f32_16x16x32_bf16 v[70:73], v[218:221], v[48:51], v[70:73]
	ds_read_b64_tr_b16 v[218:219], v173 offset:19712
	ds_read_b64_tr_b16 v[220:221], v173 offset:20800
	s_waitcnt lgkmcnt(10)
	v_mfma_f32_16x16x32_bf16 v[114:117], v[222:225], v[44:47], v[114:117]
	v_mfma_f32_16x16x32_bf16 v[66:69], v[222:225], v[48:51], v[66:69]
	ds_read_b64_tr_b16 v[222:223], v173 offset:19744
	ds_read_b64_tr_b16 v[224:225], v173 offset:20832
	s_waitcnt lgkmcnt(10)
	v_mfma_f32_16x16x32_bf16 v[158:161], v[226:229], v[38:41], v[158:161]
	v_mfma_f32_16x16x32_bf16 v[94:97], v[226:229], v[34:37], v[94:97]
	ds_read_b64_tr_b16 v[226:227], v173 offset:19776
	ds_read_b64_tr_b16 v[228:229], v173 offset:20864
	s_waitcnt lgkmcnt(10)
	v_mfma_f32_16x16x32_bf16 v[154:157], v[230:233], v[38:41], v[154:157]
	v_mfma_f32_16x16x32_bf16 v[90:93], v[230:233], v[34:37], v[90:93]
	ds_read_b64_tr_b16 v[230:231], v173 offset:19808
	ds_read_b64_tr_b16 v[232:233], v173 offset:20896
	s_waitcnt lgkmcnt(10)
	v_mfma_f32_16x16x32_bf16 v[150:153], v[236:239], v[38:41], v[150:153]
	v_mfma_f32_16x16x32_bf16 v[86:89], v[236:239], v[34:37], v[86:89]
	s_waitcnt lgkmcnt(8)
	v_mfma_f32_16x16x32_bf16 v[146:149], v[240:243], v[38:41], v[146:149]
	v_mfma_f32_16x16x32_bf16 v[82:85], v[240:243], v[34:37], v[82:85]
	s_waitcnt lgkmcnt(6)
	v_mfma_f32_16x16x32_bf16 v[142:145], v[218:221], v[38:41], v[142:145]
	v_mfma_f32_16x16x32_bf16 v[78:81], v[218:221], v[34:37], v[78:81]
	s_waitcnt lgkmcnt(4)
	v_mfma_f32_16x16x32_bf16 v[138:141], v[222:225], v[38:41], v[138:141]
	v_mfma_f32_16x16x32_bf16 v[74:77], v[222:225], v[34:37], v[74:77]
	s_waitcnt lgkmcnt(2)
	v_mfma_f32_16x16x32_bf16 v[134:137], v[226:229], v[38:41], v[134:137]
	v_mfma_f32_16x16x32_bf16 v[70:73], v[226:229], v[34:37], v[70:73]
	s_waitcnt lgkmcnt(0)
	v_mfma_f32_16x16x32_bf16 v[114:117], v[230:233], v[38:41], v[114:117]
	v_mfma_f32_16x16x32_bf16 v[66:69], v[230:233], v[34:37], v[66:69]
	s_and_saveexec_b64 s[20:21], s[22:23]
	s_cbranch_execz .LBB0_678
	v_readlane_b32 s22, v234, 45
	s_or_b64 s[18:19], s[18:19], exec
	s_nop 0
	v_mov_b32_e32 v1, s22
	ds_write_b32 v1, v200 offset:34848
	s_branch .LBB0_678
.Latt_masked:
	ds_read_b128 v[218:221], v171
	ds_read_b128 v[222:225], v171 offset:1088
	ds_read_b128 v[226:229], v171 offset:2176
	ds_read_b128 v[230:233], v171 offset:3264
	ds_read_b128 v[236:239], v171 offset:64
	ds_read_b128 v[240:243], v171 offset:1152
	ds_read_b128 v[244:247], v171 offset:2240
	ds_read_b128 v[248:251], v171 offset:3328
	v_or_b32_e32 v1, s20, v162
	v_cmp_lt_i32_e64 s[80:81], v1, v204
	v_cmp_lt_i32_e64 s[82:83], v1, v205
	s_waitcnt lgkmcnt(7)
	v_mfma_f32_16x16x32_bf16 v[34:37], v[218:221], v[98:101], 0
	v_mfma_f32_16x16x32_bf16 v[38:41], v[218:221], v[118:121], 0
	ds_read_b128 v[218:221], v171 offset:128
	s_waitcnt lgkmcnt(7)
	v_mfma_f32_16x16x32_bf16 v[42:45], v[222:225], v[98:101], 0
	v_mfma_f32_16x16x32_bf16 v[46:49], v[222:225], v[118:121], 0
	ds_read_b128 v[222:225], v171 offset:1216
	s_waitcnt lgkmcnt(7)
	v_mfma_f32_16x16x32_bf16 v[50:53], v[226:229], v[98:101], 0
	v_mfma_f32_16x16x32_bf16 v[54:57], v[226:229], v[118:121], 0
	ds_read_b128 v[226:229], v171 offset:2304
	s_waitcnt lgkmcnt(7)
	v_mfma_f32_16x16x32_bf16 v[190:193], v[230:233], v[98:101], 0
	v_mfma_f32_16x16x32_bf16 v[206:209], v[230:233], v[118:121], 0
	ds_read_b128 v[230:233], v171 offset:3392
	s_waitcnt lgkmcnt(7)
	v_mfma_f32_16x16x32_bf16 v[34:37], v[236:239], v[102:105], v[34:37]
	v_mfma_f32_16x16x32_bf16 v[38:41], v[236:239], v[122:125], v[38:41]
	ds_read_b128 v[236:239], v171 offset:192
	s_waitcnt lgkmcnt(7)
	v_mfma_f32_16x16x32_bf16 v[42:45], v[240:243], v[102:105], v[42:45]
	v_mfma_f32_16x16x32_bf16 v[46:49], v[240:243], v[122:125], v[46:49]
	ds_read_b128 v[240:243], v171 offset:1280
	s_waitcnt lgkmcnt(7)
	v_mfma_f32_16x16x32_bf16 v[50:53], v[244:247], v[102:105], v[50:53]
	v_mfma_f32_16x16x32_bf16 v[54:57], v[244:247], v[122:125], v[54:57]
	ds_read_b128 v[244:247], v171 offset:2368
	s_waitcnt lgkmcnt(7)
	v_mfma_f32_16x16x32_bf16 v[190:193], v[248:251], v[102:105], v[190:193]
	v_mfma_f32_16x16x32_bf16 v[206:209], v[248:251], v[122:125], v[206:209]
	ds_read_b128 v[248:251], v171 offset:3456
	s_waitcnt lgkmcnt(7)
	v_mfma_f32_16x16x32_bf16 v[34:37], v[218:221], v[106:109], v[34:37]
	v_mfma_f32_16x16x32_bf16 v[38:41], v[218:221], v[126:129], v[38:41]
	s_waitcnt lgkmcnt(6)
	v_mfma_f32_16x16x32_bf16 v[42:45], v[222:225], v[106:109], v[42:45]
	v_mfma_f32_16x16x32_bf16 v[46:49], v[222:225], v[126:129], v[46:49]
	s_waitcnt lgkmcnt(5)
	v_mfma_f32_16x16x32_bf16 v[50:53], v[226:229], v[106:109], v[50:53]
	v_mfma_f32_16x16x32_bf16 v[54:57], v[226:229], v[126:129], v[54:57]
	s_waitcnt lgkmcnt(4)
	v_mfma_f32_16x16x32_bf16 v[190:193], v[230:233], v[106:109], v[190:193]
	v_mfma_f32_16x16x32_bf16 v[206:209], v[230:233], v[126:129], v[206:209]
	s_waitcnt lgkmcnt(3)
	v_mfma_f32_16x16x32_bf16 v[34:37], v[236:239], v[110:113], v[34:37]
	v_mfma_f32_16x16x32_bf16 v[38:41], v[236:239], v[130:133], v[38:41]
	s_waitcnt lgkmcnt(2)
; __device__ __forceinline__ void attn_phase(const Params& p, LAS unsigned char* lds, int cidx) {
;     ...
;                     const int s0 = kt * 64 + 16 * fq, tq0 = tpos0 + fr, tq1 = tpos0 + 16 + fr;
;                     f32x2 run = (f32x2){0.f, 0.f};
; #pragma unroll
;     ...
;                         const f32x2 xv = (f32x2){st[0][idx >> 2][idx & 3], st[1][idx >> 2][idx & 3]};
;                         const f32x2 ax = __builtin_elementwise_abs(xv);
;                         f32x2 e; e.x = __builtin_amdgcn_exp2f(-ax.x); e.y = __builtin_amdgcn_exp2f(-ax.y);
;                         const f32x2 e1 = e + 1.0f;
;                         f32x2 lg; lg.x = __builtin_amdgcn_logf(e1.x); lg.y = __builtin_amdgcn_logf(e1.y);
;                         const f32x2 sp = __builtin_elementwise_max(xv, (f32x2){0.f, 0.f}) + lg;
;                         const f32x2 lw = (xv - sp) + run;
;                         st[0][idx >> 2][idx & 3] = lw.x; st[1][idx >> 2][idx & 3] = lw.y;
;                         f32x2 dec; dec.x = (s0 + idx) < tq0 ? sp.x : 0.f; dec.y = (s0 + idx) < tq1 ? sp.y : 0.f;
;                         run = run - dec;
;                     }
	v_mfma_f32_16x16x32_bf16 v[42:45], v[240:243], v[110:113], v[42:45]
	v_mfma_f32_16x16x32_bf16 v[46:49], v[240:243], v[130:133], v[46:49]
	s_waitcnt lgkmcnt(1)
	v_mfma_f32_16x16x32_bf16 v[50:53], v[244:247], v[110:113], v[50:53]
	v_mfma_f32_16x16x32_bf16 v[54:57], v[244:247], v[130:133], v[54:57]
	s_waitcnt lgkmcnt(0)
	v_mfma_f32_16x16x32_bf16 v[190:193], v[248:251], v[110:113], v[190:193]
	v_mfma_f32_16x16x32_bf16 v[206:209], v[248:251], v[130:133], v[206:209]
	s_nop 6
	v_exp_f32_e64 v62, -|v193|
	v_mov_b32_e32 v60, v193
	v_exp_f32_e64 v63, -|v209|
	v_max_f32_e32 v65, 0, v209
	v_pk_add_f32 v[62:63], v[62:63], 1.0 op_sel_hi:[1,0]
	v_max_f32_e32 v64, 0, v193
	v_log_f32_e32 v62, v62
	v_log_f32_e32 v63, v63
	v_mov_b32_e32 v61, v209
	v_mov_b32_e32 v193, v208
	v_pk_add_f32 v[62:63], v[64:65], v[62:63]
	v_or_b32_e32 v64, 15, v1
	v_cmp_lt_i32_e64 s[18:19], v64, v204
	v_cmp_lt_i32_e32 vcc, v64, v205
	v_pk_add_f32 v[60:61], v[60:61], v[62:63] neg_lo:[0,1] neg_hi:[0,1]
	v_cndmask_b32_e64 v62, 0, v62, s[18:19]
	v_cndmask_b32_e32 v63, 0, v63, vcc
	v_pk_add_f32 v[64:65], v[62:63], 0 op_sel_hi:[1,0] neg_lo:[1,0] neg_hi:[1,0]
	v_exp_f32_e64 v62, -|v192|
	v_exp_f32_e64 v63, -|v208|
	v_max_f32_e32 v209, 0, v208
	v_pk_add_f32 v[62:63], v[62:63], 1.0 op_sel_hi:[1,0]
	v_max_f32_e32 v208, 0, v192
	v_log_f32_e32 v62, v62
	v_log_f32_e32 v63, v63
	v_pk_add_f32 v[60:61], v[60:61], 0 op_sel_hi:[1,0]
	v_pk_add_f32 v[208:209], v[208:209], v[62:63]
	s_nop 0
	v_pk_add_f32 v[62:63], v[192:193], v[208:209] neg_lo:[0,1] neg_hi:[0,1]
	v_or_b32_e32 v193, 14, v1
	v_cmp_lt_i32_e64 s[22:23], v193, v204
	v_cmp_lt_i32_e64 s[20:21], v193, v205
	v_pk_add_f32 v[62:63], v[62:63], v[64:65]
	v_cndmask_b32_e64 v192, 0, v208, s[22:23]
	v_cndmask_b32_e64 v193, 0, v209, s[20:21]
	v_exp_f32_e64 v208, -|v191|
	v_exp_f32_e64 v209, -|v207|
	v_pk_add_f32 v[192:193], v[64:65], v[192:193] neg_lo:[0,1] neg_hi:[0,1]
	v_mov_b32_e32 v64, v191
	v_mov_b32_e32 v65, v207
	v_pk_add_f32 v[208:209], v[208:209], 1.0 op_sel_hi:[1,0]
	v_log_f32_e32 v208, v208
	v_log_f32_e32 v209, v209
	v_max_f32_e32 v211, 0, v207
	v_max_f32_e32 v210, 0, v191
	v_or_b32_e32 v191, 13, v1
	v_pk_add_f32 v[208:209], v[210:211], v[208:209]
	v_cmp_lt_i32_e64 s[26:27], v191, v204
	v_cmp_lt_i32_e64 s[24:25], v191, v205
	v_pk_add_f32 v[64:65], v[64:65], v[208:209] neg_lo:[0,1] neg_hi:[0,1]
	v_cndmask_b32_e64 v208, 0, v208, s[26:27]
	v_cndmask_b32_e64 v209, 0, v209, s[24:25]
	v_pk_add_f32 v[64:65], v[64:65], v[192:193]
	v_pk_add_f32 v[192:193], v[192:193], v[208:209] neg_lo:[0,1] neg_hi:[0,1]
	v_exp_f32_e64 v208, -|v190|
	v_exp_f32_e64 v209, -|v206|
	v_mov_b32_e32 v191, v206
	v_max_f32_e32 v207, 0, v206
	v_pk_add_f32 v[208:209], v[208:209], 1.0 op_sel_hi:[1,0]
	v_log_f32_e32 v208, v208
	v_log_f32_e32 v209, v209
	v_max_f32_e32 v206, 0, v190
	v_pk_add_f32 v[206:207], v[206:207], v[208:209]
	v_or_b32_e32 v208, 12, v1
	v_cmp_lt_i32_e64 s[28:29], v208, v204
	v_cmp_lt_i32_e64 s[30:31], v208, v205
	v_exp_f32_e64 v208, -|v53|
	v_exp_f32_e64 v209, -|v57|
	v_pk_add_f32 v[190:191], v[190:191], v[206:207] neg_lo:[0,1] neg_hi:[0,1]
	v_cndmask_b32_e64 v206, 0, v206, s[28:29]
	v_cndmask_b32_e64 v207, 0, v207, s[30:31]
	v_pk_add_f32 v[208:209], v[208:209], 1.0 op_sel_hi:[1,0]
	v_pk_add_f32 v[190:191], v[190:191], v[192:193]
	v_log_f32_e32 v208, v208
	v_log_f32_e32 v209, v209
	v_pk_add_f32 v[206:207], v[192:193], v[206:207] neg_lo:[0,1] neg_hi:[0,1]
	v_mov_b32_e32 v192, v53
	v_mov_b32_e32 v193, v57
	v_max_f32_e32 v211, 0, v57
	v_max_f32_e32 v210, 0, v53
	v_or_b32_e32 v53, 11, v1
	v_pk_add_f32 v[208:209], v[210:211], v[208:209]
	v_cmp_lt_i32_e64 s[36:37], v53, v204
	v_cmp_lt_i32_e64 s[34:35], v53, v205
	v_pk_add_f32 v[192:193], v[192:193], v[208:209] neg_lo:[0,1] neg_hi:[0,1]
	v_cndmask_b32_e64 v208, 0, v208, s[36:37]
	v_cndmask_b32_e64 v209, 0, v209, s[34:35]
	v_pk_add_f32 v[192:193], v[192:193], v[206:207]
	v_pk_add_f32 v[206:207], v[206:207], v[208:209] neg_lo:[0,1] neg_hi:[0,1]
	v_exp_f32_e64 v208, -|v52|
	v_exp_f32_e64 v209, -|v56|
	v_mov_b32_e32 v53, v56
	v_max_f32_e32 v57, 0, v56
	v_pk_add_f32 v[208:209], v[208:209], 1.0 op_sel_hi:[1,0]
	v_log_f32_e32 v208, v208
	v_log_f32_e32 v209, v209
	v_max_f32_e32 v56, 0, v52
	v_pk_add_f32 v[56:57], v[56:57], v[208:209]
	v_or_b32_e32 v208, 10, v1
	v_cmp_lt_i32_e64 s[40:41], v208, v204
	v_cmp_lt_i32_e64 s[38:39], v208, v205
	v_exp_f32_e64 v208, -|v51|
	v_exp_f32_e64 v209, -|v55|
	v_pk_add_f32 v[52:53], v[52:53], v[56:57] neg_lo:[0,1] neg_hi:[0,1]
	v_cndmask_b32_e64 v56, 0, v56, s[40:41]
	v_cndmask_b32_e64 v57, 0, v57, s[38:39]
	v_pk_add_f32 v[208:209], v[208:209], 1.0 op_sel_hi:[1,0]
	v_pk_add_f32 v[52:53], v[52:53], v[206:207]
	v_log_f32_e32 v208, v208
	v_log_f32_e32 v209, v209
	v_pk_add_f32 v[206:207], v[206:207], v[56:57] neg_lo:[0,1] neg_hi:[0,1]
	v_mov_b32_e32 v56, v51
	v_mov_b32_e32 v57, v55
	v_max_f32_e32 v211, 0, v55
	v_max_f32_e32 v210, 0, v51
	v_or_b32_e32 v51, 9, v1
	v_pk_add_f32 v[208:209], v[210:211], v[208:209]
	v_cmp_lt_i32_e64 s[44:45], v51, v204
	v_cmp_lt_i32_e64 s[42:43], v51, v205
	v_pk_add_f32 v[56:57], v[56:57], v[208:209] neg_lo:[0,1] neg_hi:[0,1]
	v_cndmask_b32_e64 v208, 0, v208, s[44:45]
	v_cndmask_b32_e64 v209, 0, v209, s[42:43]
	v_pk_add_f32 v[56:57], v[56:57], v[206:207]
	v_pk_add_f32 v[206:207], v[206:207], v[208:209] neg_lo:[0,1] neg_hi:[0,1]
	v_exp_f32_e64 v208, -|v50|
	v_exp_f32_e64 v209, -|v54|
	v_mov_b32_e32 v51, v54
	v_max_f32_e32 v55, 0, v54
	v_pk_add_f32 v[208:209], v[208:209], 1.0 op_sel_hi:[1,0]
	v_log_f32_e32 v208, v208
	v_log_f32_e32 v209, v209
	v_max_f32_e32 v54, 0, v50
	v_pk_add_f32 v[54:55], v[54:55], v[208:209]
	v_or_b32_e32 v208, 8, v1
	v_cmp_lt_i32_e64 s[48:49], v208, v204
; __device__ __forceinline__ void attn_phase(const Params& p, LAS unsigned char* lds, int cidx) {
;     ...
;                     const int s0 = kt * 64 + 16 * fq, tq0 = tpos0 + fr, tq1 = tpos0 + 16 + fr;
;                     f32x2 run = (f32x2){0.f, 0.f};
; #pragma unroll
;     ...
;                         const f32x2 xv = (f32x2){st[0][idx >> 2][idx & 3], st[1][idx >> 2][idx & 3]};
;                         const f32x2 ax = __builtin_elementwise_abs(xv);
;                         f32x2 e; e.x = __builtin_amdgcn_exp2f(-ax.x); e.y = __builtin_amdgcn_exp2f(-ax.y);
;                         const f32x2 e1 = e + 1.0f;
;                         f32x2 lg; lg.x = __builtin_amdgcn_logf(e1.x); lg.y = __builtin_amdgcn_logf(e1.y);
;                         const f32x2 sp = __builtin_elementwise_max(xv, (f32x2){0.f, 0.f}) + lg;
;                         const f32x2 lw = (xv - sp) + run;
;                         st[0][idx >> 2][idx & 3] = lw.x; st[1][idx >> 2][idx & 3] = lw.y;
;                         f32x2 dec; dec.x = (s0 + idx) < tq0 ? sp.x : 0.f; dec.y = (s0 + idx) < tq1 ? sp.y : 0.f;
;                         run = run - dec;
;                     }
	v_cmp_lt_i32_e64 s[46:47], v208, v205
	v_exp_f32_e64 v208, -|v45|
	v_exp_f32_e64 v209, -|v49|
	v_pk_add_f32 v[50:51], v[50:51], v[54:55] neg_lo:[0,1] neg_hi:[0,1]
	v_cndmask_b32_e64 v54, 0, v54, s[48:49]
	v_cndmask_b32_e64 v55, 0, v55, s[46:47]
	v_pk_add_f32 v[208:209], v[208:209], 1.0 op_sel_hi:[1,0]
	v_pk_add_f32 v[50:51], v[50:51], v[206:207]
	v_log_f32_e32 v208, v208
	v_log_f32_e32 v209, v209
	v_pk_add_f32 v[206:207], v[206:207], v[54:55] neg_lo:[0,1] neg_hi:[0,1]
	v_mov_b32_e32 v54, v45
	v_mov_b32_e32 v55, v49
	v_max_f32_e32 v211, 0, v49
	v_max_f32_e32 v210, 0, v45
	v_or_b32_e32 v45, 7, v1
	v_pk_add_f32 v[208:209], v[210:211], v[208:209]
	v_cmp_lt_i32_e64 s[52:53], v45, v204
	v_cmp_lt_i32_e64 s[50:51], v45, v205
	v_pk_add_f32 v[54:55], v[54:55], v[208:209] neg_lo:[0,1] neg_hi:[0,1]
	v_cndmask_b32_e64 v208, 0, v208, s[52:53]
	v_cndmask_b32_e64 v209, 0, v209, s[50:51]
	v_pk_add_f32 v[54:55], v[54:55], v[206:207]
	v_pk_add_f32 v[206:207], v[206:207], v[208:209] neg_lo:[0,1] neg_hi:[0,1]
	v_exp_f32_e64 v208, -|v44|
	v_exp_f32_e64 v209, -|v48|
	v_mov_b32_e32 v45, v48
	v_max_f32_e32 v49, 0, v48
	v_pk_add_f32 v[208:209], v[208:209], 1.0 op_sel_hi:[1,0]
	v_log_f32_e32 v208, v208
	v_log_f32_e32 v209, v209
	v_max_f32_e32 v48, 0, v44
	v_pk_add_f32 v[48:49], v[48:49], v[208:209]
	v_or_b32_e32 v208, 6, v1
	v_cmp_lt_i32_e64 s[56:57], v208, v204
	v_cmp_lt_i32_e64 s[54:55], v208, v205
	v_exp_f32_e64 v208, -|v43|
	v_exp_f32_e64 v209, -|v47|
	v_pk_add_f32 v[44:45], v[44:45], v[48:49] neg_lo:[0,1] neg_hi:[0,1]
	v_cndmask_b32_e64 v48, 0, v48, s[56:57]
	v_cndmask_b32_e64 v49, 0, v49, s[54:55]
	v_pk_add_f32 v[208:209], v[208:209], 1.0 op_sel_hi:[1,0]
	v_pk_add_f32 v[44:45], v[44:45], v[206:207]
	v_log_f32_e32 v208, v208
	v_log_f32_e32 v209, v209
	v_pk_add_f32 v[206:207], v[206:207], v[48:49] neg_lo:[0,1] neg_hi:[0,1]
	v_mov_b32_e32 v48, v43
	v_mov_b32_e32 v49, v47
	v_max_f32_e32 v211, 0, v47
	v_max_f32_e32 v210, 0, v43
	v_or_b32_e32 v43, 5, v1
	v_pk_add_f32 v[208:209], v[210:211], v[208:209]
	v_cmp_lt_i32_e64 s[60:61], v43, v204
	v_cmp_lt_i32_e64 s[58:59], v43, v205
	v_pk_add_f32 v[48:49], v[48:49], v[208:209] neg_lo:[0,1] neg_hi:[0,1]
	v_cndmask_b32_e64 v208, 0, v208, s[60:61]
	v_cndmask_b32_e64 v209, 0, v209, s[58:59]
	v_pk_add_f32 v[48:49], v[48:49], v[206:207]
	v_pk_add_f32 v[206:207], v[206:207], v[208:209] neg_lo:[0,1] neg_hi:[0,1]
	v_exp_f32_e64 v208, -|v42|
	v_exp_f32_e64 v209, -|v46|
	v_mov_b32_e32 v43, v46
	v_max_f32_e32 v47, 0, v46
	v_pk_add_f32 v[208:209], v[208:209], 1.0 op_sel_hi:[1,0]
	v_log_f32_e32 v208, v208
	v_log_f32_e32 v209, v209
	v_max_f32_e32 v46, 0, v42
	v_pk_add_f32 v[208:209], v[46:47], v[208:209]
	s_nop 0
	v_pk_add_f32 v[42:43], v[42:43], v[208:209] neg_lo:[0,1] neg_hi:[0,1]
	s_nop 0
	v_pk_add_f32 v[46:47], v[42:43], v[206:207]
	v_or_b32_e32 v43, 4, v1
	v_cmp_lt_i32_e64 s[64:65], v43, v204
	v_cmp_lt_i32_e64 s[62:63], v43, v205
	s_nop 0
	v_cndmask_b32_e64 v42, 0, v208, s[64:65]
	v_cndmask_b32_e64 v43, 0, v209, s[62:63]
	v_exp_f32_e64 v208, -|v37|
	v_exp_f32_e64 v209, -|v41|
	v_pk_add_f32 v[42:43], v[206:207], v[42:43] neg_lo:[0,1] neg_hi:[0,1]
	v_mov_b32_e32 v206, v37
	v_mov_b32_e32 v207, v41
	v_pk_add_f32 v[208:209], v[208:209], 1.0 op_sel_hi:[1,0]
	v_log_f32_e32 v208, v208
	v_log_f32_e32 v209, v209
	v_max_f32_e32 v211, 0, v41
	v_max_f32_e32 v210, 0, v37
	v_or_b32_e32 v37, 3, v1
	v_pk_add_f32 v[208:209], v[210:211], v[208:209]
	v_cmp_lt_i32_e64 s[68:69], v37, v204
	v_cmp_lt_i32_e64 s[66:67], v37, v205
	v_pk_add_f32 v[206:207], v[206:207], v[208:209] neg_lo:[0,1] neg_hi:[0,1]
	v_cndmask_b32_e64 v208, 0, v208, s[68:69]
	v_cndmask_b32_e64 v209, 0, v209, s[66:67]
	v_pk_add_f32 v[206:207], v[206:207], v[42:43]
	v_pk_add_f32 v[42:43], v[42:43], v[208:209] neg_lo:[0,1] neg_hi:[0,1]
	v_exp_f32_e64 v208, -|v36|
	v_exp_f32_e64 v209, -|v40|
	v_mov_b32_e32 v37, v40
	v_max_f32_e32 v41, 0, v40
	v_pk_add_f32 v[208:209], v[208:209], 1.0 op_sel_hi:[1,0]
	v_log_f32_e32 v208, v208
	v_log_f32_e32 v209, v209
	v_max_f32_e32 v40, 0, v36
	v_pk_add_f32 v[40:41], v[40:41], v[208:209]
	v_or_b32_e32 v208, 2, v1
	v_cmp_lt_i32_e64 s[72:73], v208, v204
	v_cmp_lt_i32_e64 s[70:71], v208, v205
	v_exp_f32_e64 v208, -|v35|
	v_exp_f32_e64 v209, -|v39|
	v_pk_add_f32 v[36:37], v[36:37], v[40:41] neg_lo:[0,1] neg_hi:[0,1]
	v_cndmask_b32_e64 v40, 0, v40, s[72:73]
	v_cndmask_b32_e64 v41, 0, v41, s[70:71]
	v_pk_add_f32 v[208:209], v[208:209], 1.0 op_sel_hi:[1,0]
	v_pk_add_f32 v[36:37], v[36:37], v[42:43]
	v_log_f32_e32 v208, v208
	v_log_f32_e32 v209, v209
	v_pk_add_f32 v[40:41], v[42:43], v[40:41] neg_lo:[0,1] neg_hi:[0,1]
	v_mov_b32_e32 v42, v35
	v_mov_b32_e32 v43, v39
	v_max_f32_e32 v211, 0, v39
	v_max_f32_e32 v210, 0, v35
	v_pk_add_f32 v[208:209], v[210:211], v[208:209]
	v_or_b32_e32 v35, 1, v1
	v_pk_add_f32 v[42:43], v[42:43], v[208:209] neg_lo:[0,1] neg_hi:[0,1]
	v_cmp_lt_i32_e64 s[76:77], v35, v204
	v_cmp_lt_i32_e64 s[74:75], v35, v205
	v_pk_add_f32 v[210:211], v[42:43], v[40:41]
	v_cndmask_b32_e64 v42, 0, v208, s[76:77]
	v_cndmask_b32_e64 v43, 0, v209, s[74:75]
	v_pk_add_f32 v[40:41], v[40:41], v[42:43] neg_lo:[0,1] neg_hi:[0,1]
	v_exp_f32_e64 v42, -|v34|
	v_exp_f32_e64 v43, -|v38|
	v_mov_b32_e32 v35, v38
	v_max_f32_e32 v39, 0, v38
	v_pk_add_f32 v[42:43], v[42:43], 1.0 op_sel_hi:[1,0]
	v_log_f32_e32 v42, v42
	v_log_f32_e32 v43, v43
	v_max_f32_e32 v38, 0, v34
	v_or_b32_e32 v1, v201, v196
	v_lshlrev_b32_e32 v1, 2, v1
	v_pk_add_f32 v[38:39], v[38:39], v[42:43]
	v_xor_b32_e32 v1, 0x80, v1
	v_pk_add_f32 v[34:35], v[34:35], v[38:39] neg_lo:[0,1] neg_hi:[0,1]
	v_cndmask_b32_e64 v38, 0, v38, s[80:81]
	v_cndmask_b32_e64 v39, 0, v39, s[82:83]
	v_pk_add_f32 v[38:39], v[40:41], v[38:39] neg_lo:[0,1] neg_hi:[0,1]
	v_pk_add_f32 v[34:35], v[34:35], v[40:41]
	ds_bpermute_b32 v40, v202, v38
	ds_bpermute_b32 v41, v202, v39
	ds_bpermute_b32 v42, v1, v38
	ds_bpermute_b32 v43, v1, v39
	ds_bpermute_b32 v208, v203, v38
	ds_bpermute_b32 v209, v203, v39
	s_waitcnt lgkmcnt(4)
; #define LAS __attribute__((address_space(3)))
; __device__ __forceinline__ void attn_phase(const Params& p, LAS unsigned char* lds, int cidx) {
;     ...
;                     f32x2 t16, t32, t48;
;                     t16.x = __shfl(run.x, (lane + 16) & 63); t16.y = __shfl(run.y, (lane + 16) & 63);
;                     t32.x = __shfl(run.x, (lane + 32) & 63); t32.y = __shfl(run.y, (lane + 32) & 63);
;                     t48.x = __shfl(run.x, (lane + 48) & 63); t48.y = __shfl(run.y, (lane + 48) & 63);
;                     const f32x2 z2 = (f32x2){0.f, 0.f};
;                     const f32x2 higher = (fq < 3 ? t16 : z2) + (fq < 2 ? t32 : z2) + (fq < 1 ? t48 : z2);
;                     const f32x2 base = (f32x2){C[0], C[1]} + higher;
;                     const f32x2 tot = (run + t16) + (t32 + t48);
;                     C[0] += tot.x; C[1] += tot.y;
;                     float w0[16], w1[16];
; #pragma unroll
;                     for (int idx = 0; idx < 16; ++idx) {
;                         const f32x2 a2 = (f32x2){st[0][idx >> 2][idx & 3], st[1][idx >> 2][idx & 3]} + base;
;                         w0[idx] = (s0 + idx) < tq0 ? __builtin_amdgcn_exp2f(a2.x) : 0.f;
;                         w1[idx] = (s0 + idx) < tq1 ? __builtin_amdgcn_exp2f(a2.y) : 0.f;
;                     }
; #pragma unroll
;                     for (int k2 = 0; k2 < 2; ++k2) {
;                         u32x4 pw; pw.x = cvt_pk_bf16(w0[8 * k2 + 0], w0[8 * k2 + 1]); pw.y = cvt_pk_bf16(w0[8 * k2 + 2], w0[8 * k2 + 3]); pw.z = cvt_pk_bf16(w0[8 * k2 + 4], w0[8 * k2 + 5]); pw.w = cvt_pk_bf16(w0[8 * k2 + 6], w0[8 * k2 + 7]);
;                         pb[0][k2] = __builtin_bit_cast(bf16x8, pw);
;                         u32x4 pv; pv.x = cvt_pk_bf16(w1[8 * k2 + 0], w1[8 * k2 + 1]); pv.y = cvt_pk_bf16(w1[8 * k2 + 2], w1[8 * k2 + 3]); pv.z = cvt_pk_bf16(w1[8 * k2 + 4], w1[8 * k2 + 5]); pv.w = cvt_pk_bf16(w1[8 * k2 + 6], w1[8 * k2 + 7]);
;                         pb[1][k2] = __builtin_bit_cast(bf16x8, pv);
;                     }
;                 }
; #pragma unroll
;                 for (int k2 = 0; k2 < 2; ++k2)
; #pragma unroll
;                     for (int dt = 0; dt < 8; ++dt) {
;                         const LAS bf16_t* a0 = Vl + (16 * fq + 8 * k2 + (fr >> 2)) * AT_P + 16 * dt + 4 * (fr & 3);
	v_cndmask_b32_e64 v213, v41, 0, s[8:9]
	v_cndmask_b32_e64 v212, v40, 0, s[8:9]
	s_waitcnt lgkmcnt(2)
	v_cndmask_b32_e64 v215, 0, v43, s[10:11]
	v_cndmask_b32_e64 v214, 0, v42, s[10:11]
	v_pk_add_f32 v[212:213], v[212:213], v[214:215]
	s_waitcnt lgkmcnt(0)
	v_cndmask_b32_e64 v215, 0, v209, s[12:13]
	v_cndmask_b32_e64 v214, 0, v208, s[12:13]
	v_pk_add_f32 v[212:213], v[212:213], v[214:215]
	v_pk_add_f32 v[38:39], v[38:39], v[40:41]
	v_pk_add_f32 v[212:213], v[58:59], v[212:213]
	v_pk_add_f32 v[40:41], v[42:43], v[208:209]
	v_pk_add_f32 v[34:35], v[212:213], v[34:35]
	v_pk_add_f32 v[42:43], v[40:41], v[38:39]
	v_exp_f32_e32 v1, v34
	v_exp_f32_e32 v34, v35
	v_pk_add_f32 v[58:59], v[58:59], v[42:43]
	v_cndmask_b32_e64 v1, 0, v1, s[80:81]
	v_cndmask_b32_e64 v38, 0, v34, s[82:83]
	v_pk_add_f32 v[34:35], v[212:213], v[210:211]
	s_nop 0
	v_exp_f32_e32 v34, v34
	s_nop 0
	v_cndmask_b32_e64 v39, 0, v34, s[76:77]
	v_exp_f32_e32 v34, v35
	s_nop 0
	v_cndmask_b32_e64 v40, 0, v34, s[74:75]
	v_pk_add_f32 v[34:35], v[212:213], v[36:37]
	s_nop 0
	v_exp_f32_e32 v34, v34
	s_nop 0
	v_cndmask_b32_e64 v36, 0, v34, s[72:73]
	v_exp_f32_e32 v34, v35
	s_nop 0
	v_cndmask_b32_e64 v37, 0, v34, s[70:71]
	v_pk_add_f32 v[34:35], v[212:213], v[206:207]
	s_nop 0
	v_exp_f32_e32 v34, v34
	s_nop 0
	v_cndmask_b32_e64 v41, 0, v34, s[68:69]
	v_exp_f32_e32 v34, v35
	s_nop 0
	v_cndmask_b32_e64 v206, 0, v34, s[66:67]
	v_pk_add_f32 v[34:35], v[212:213], v[46:47]
	s_nop 0
	v_exp_f32_e32 v34, v34
	s_nop 0
	v_cndmask_b32_e64 v46, 0, v34, s[64:65]
	v_exp_f32_e32 v34, v35
	s_nop 0
	v_cndmask_b32_e64 v207, 0, v34, s[62:63]
	v_pk_add_f32 v[34:35], v[212:213], v[48:49]
	s_nop 0
	v_exp_f32_e32 v34, v34
	s_nop 0
	v_cndmask_b32_e64 v47, 0, v34, s[60:61]
	v_exp_f32_e32 v34, v35
	s_nop 0
	v_cndmask_b32_e64 v208, 0, v34, s[58:59]
	v_pk_add_f32 v[34:35], v[212:213], v[44:45]
	v_cvt_pk_bf16_f32 v44, v1, v39
	v_cvt_pk_bf16_f32 v45, v36, v41
	v_cvt_pk_bf16_f32 v46, v46, v47
	s_nop 0
	v_exp_f32_e32 v34, v34
	s_nop 0
	v_cndmask_b32_e64 v48, 0, v34, s[56:57]
	v_exp_f32_e32 v34, v35
	s_nop 0
	v_cndmask_b32_e64 v209, 0, v34, s[54:55]
	v_pk_add_f32 v[34:35], v[212:213], v[54:55]
	s_nop 0
	v_exp_f32_e32 v34, v34
	s_nop 0
	v_cndmask_b32_e64 v49, 0, v34, s[52:53]
	v_exp_f32_e32 v34, v35
	v_cvt_pk_bf16_f32 v47, v48, v49
	v_cvt_pk_bf16_f32 v48, v38, v40
	v_cvt_pk_bf16_f32 v49, v37, v206
	s_nop 0
	v_cndmask_b32_e64 v54, 0, v34, s[50:51]
	v_pk_add_f32 v[34:35], v[212:213], v[50:51]
	v_cvt_pk_bf16_f32 v50, v207, v208
	v_cvt_pk_bf16_f32 v51, v209, v54
	s_nop 0
	v_exp_f32_e32 v34, v34
	s_nop 0
	v_cndmask_b32_e64 v55, 0, v34, s[48:49]
	v_exp_f32_e32 v34, v35
	s_nop 0
	v_cndmask_b32_e64 v210, 0, v34, s[46:47]
	v_pk_add_f32 v[34:35], v[212:213], v[56:57]
	s_nop 0
	v_exp_f32_e32 v34, v34
	s_nop 0
	v_cndmask_b32_e64 v56, 0, v34, s[44:45]
	v_exp_f32_e32 v34, v35
	v_cvt_pk_bf16_f32 v38, v55, v56
	s_nop 0
	v_cndmask_b32_e64 v57, 0, v34, s[42:43]
	v_pk_add_f32 v[34:35], v[212:213], v[52:53]
	s_nop 0
	v_exp_f32_e32 v34, v34
	s_nop 0
	v_cndmask_b32_e64 v52, 0, v34, s[40:41]
	v_exp_f32_e32 v34, v35
	s_nop 0
	v_cndmask_b32_e64 v53, 0, v34, s[38:39]
	v_pk_add_f32 v[34:35], v[212:213], v[192:193]
	s_nop 0
	v_exp_f32_e32 v34, v34
	s_nop 0
	v_cndmask_b32_e64 v192, 0, v34, s[36:37]
	v_exp_f32_e32 v34, v35
	v_cvt_pk_bf16_f32 v39, v52, v192
	s_nop 0
	v_cndmask_b32_e64 v193, 0, v34, s[34:35]
	v_pk_add_f32 v[34:35], v[212:213], v[190:191]
	s_nop 0
	v_exp_f32_e32 v34, v34
	s_nop 0
	v_cndmask_b32_e64 v190, 0, v34, s[28:29]
	v_exp_f32_e32 v34, v35
	s_nop 0
	v_cndmask_b32_e64 v191, 0, v34, s[30:31]
	v_pk_add_f32 v[34:35], v[212:213], v[64:65]
	s_nop 0
	v_exp_f32_e32 v34, v34
	s_nop 0
	v_cndmask_b32_e64 v64, 0, v34, s[26:27]
	v_exp_f32_e32 v34, v35
	v_cvt_pk_bf16_f32 v40, v190, v64
	s_nop 0
	v_cndmask_b32_e64 v65, 0, v34, s[24:25]
	v_pk_add_f32 v[34:35], v[212:213], v[62:63]
	s_nop 0
	v_exp_f32_e32 v34, v34
	s_nop 0
	v_cndmask_b32_e64 v62, 0, v34, s[22:23]
	v_exp_f32_e32 v34, v35
	s_nop 0
	v_cndmask_b32_e64 v63, 0, v34, s[20:21]
	v_pk_add_f32 v[34:35], v[212:213], v[60:61]
	v_readlane_b32 s20, v234, 43
	v_exp_f32_e32 v34, v34
	v_exp_f32_e32 v35, v35
	v_readlane_b32 s21, v234, 44
	v_cndmask_b32_e64 v34, 0, v34, s[18:19]
	v_cndmask_b32_e32 v60, 0, v35, vcc
	v_cvt_pk_bf16_f32 v41, v62, v34
	v_cvt_pk_bf16_f32 v34, v210, v57
	v_cvt_pk_bf16_f32 v35, v53, v193
	v_cvt_pk_bf16_f32 v36, v191, v65
	v_cvt_pk_bf16_f32 v37, v63, v60
	ds_read_b64_tr_b16 v[218:219], v173 offset:17408
	ds_read_b64_tr_b16 v[220:221], v173 offset:18496
	ds_read_b64_tr_b16 v[222:223], v173 offset:17440
	ds_read_b64_tr_b16 v[224:225], v173 offset:18528
	ds_read_b64_tr_b16 v[226:227], v173 offset:17472
	ds_read_b64_tr_b16 v[228:229], v173 offset:18560
	ds_read_b64_tr_b16 v[230:231], v173 offset:17504
	ds_read_b64_tr_b16 v[232:233], v173 offset:18592
	ds_read_b64_tr_b16 v[236:237], v173 offset:17536
	ds_read_b64_tr_b16 v[238:239], v173 offset:18624
	ds_read_b64_tr_b16 v[240:241], v173 offset:17568
	ds_read_b64_tr_b16 v[242:243], v173 offset:18656
	s_mov_b32 s18, 0xc3200000
	v_cmp_gt_f32_e32 vcc, s18, v58
	v_cmp_gt_f32_e64 s[18:19], s18, v59
	s_waitcnt lgkmcnt(10)
; #define LAS __attribute__((address_space(3)))
; __device__ __forceinline__ void attn_phase(const Params& p, LAS unsigned char* lds, int cidx) {
;     ...
; #pragma unroll
;                 for (int k2 = 0; k2 < 2; ++k2)
; #pragma unroll
;                     for (int dt = 0; dt < 8; ++dt) {
;                         const LAS bf16_t* a0 = Vl + (16 * fq + 8 * k2 + (fr >> 2)) * AT_P + 16 * dt + 4 * (fr & 3);
;                         const s16x4 lo = __builtin_amdgcn_ds_read_tr16_b64_v4i16((LAS s16x4*)a0), hi = __builtin_amdgcn_ds_read_tr16_b64_v4i16((LAS s16x4*)(a0 + 4 * AT_P));
;                         const bf16x8 vf = (bf16x8){lo[0], lo[1], lo[2], lo[3], hi[0], hi[1], hi[2], hi[3]};
;                         o[0][dt] = __builtin_amdgcn_mfma_f32_16x16x32_bf16(vf, pb[0][k2], o[0][dt], 0, 0, 0);
;                         o[1][dt] = __builtin_amdgcn_mfma_f32_16x16x32_bf16(vf, pb[1][k2], o[1][dt], 0, 0, 0);
;                     }
;                 if (__builtin_amdgcn_ballot_w64(C[0] < -160.f && C[1] < -160.f) == ~0ull) { wdone = true;     if (lane == 0) misc[8 + wid] = 1; }
	v_mfma_f32_16x16x32_bf16 v[158:161], v[218:221], v[44:47], v[158:161]
	v_mfma_f32_16x16x32_bf16 v[94:97], v[218:221], v[48:51], v[94:97]
	ds_read_b64_tr_b16 v[218:219], v173 offset:17600
	ds_read_b64_tr_b16 v[220:221], v173 offset:18688
	s_and_b64 s[18:19], vcc, s[18:19]
	v_cndmask_b32_e64 v1, 0, 1, s[18:19]
	s_waitcnt lgkmcnt(10)
	v_mfma_f32_16x16x32_bf16 v[154:157], v[222:225], v[44:47], v[154:157]
	v_mfma_f32_16x16x32_bf16 v[90:93], v[222:225], v[48:51], v[90:93]
	ds_read_b64_tr_b16 v[222:223], v173 offset:17632
	ds_read_b64_tr_b16 v[224:225], v173 offset:18720
	v_cmp_ne_u32_e32 vcc, 0, v1
	s_cmp_eq_u64 vcc, -1
	s_cselect_b64 s[18:19], -1, 0
	s_waitcnt lgkmcnt(10)
	v_mfma_f32_16x16x32_bf16 v[150:153], v[226:229], v[44:47], v[150:153]
	v_mfma_f32_16x16x32_bf16 v[86:89], v[226:229], v[48:51], v[86:89]
	ds_read_b64_tr_b16 v[226:227], v173 offset:19584
	ds_read_b64_tr_b16 v[228:229], v173 offset:20672
	s_and_b64 s[22:23], s[20:21], s[18:19]
	s_waitcnt lgkmcnt(10)
	v_mfma_f32_16x16x32_bf16 v[146:149], v[230:233], v[44:47], v[146:149]
	v_mfma_f32_16x16x32_bf16 v[82:85], v[230:233], v[48:51], v[82:85]
	ds_read_b64_tr_b16 v[230:231], v173 offset:19616
	ds_read_b64_tr_b16 v[232:233], v173 offset:20704
	s_waitcnt lgkmcnt(10)
	v_mfma_f32_16x16x32_bf16 v[142:145], v[236:239], v[44:47], v[142:145]
	v_mfma_f32_16x16x32_bf16 v[78:81], v[236:239], v[48:51], v[78:81]
	ds_read_b64_tr_b16 v[236:237], v173 offset:19648
	ds_read_b64_tr_b16 v[238:239], v173 offset:20736
	s_waitcnt lgkmcnt(10)
	v_mfma_f32_16x16x32_bf16 v[138:141], v[240:243], v[44:47], v[138:141]
	v_mfma_f32_16x16x32_bf16 v[74:77], v[240:243], v[48:51], v[74:77]
	ds_read_b64_tr_b16 v[240:241], v173 offset:19680
	ds_read_b64_tr_b16 v[242:243], v173 offset:20768
	s_waitcnt lgkmcnt(10)
	v_mfma_f32_16x16x32_bf16 v[134:137], v[218:221], v[44:47], v[134:137]
	v_mfma_f32_16x16x32_bf16 v[70:73], v[218:221], v[48:51], v[70:73]
	ds_read_b64_tr_b16 v[218:219], v173 offset:19712
	ds_read_b64_tr_b16 v[220:221], v173 offset:20800
	s_waitcnt lgkmcnt(10)
	v_mfma_f32_16x16x32_bf16 v[114:117], v[222:225], v[44:47], v[114:117]
	v_mfma_f32_16x16x32_bf16 v[66:69], v[222:225], v[48:51], v[66:69]
	ds_read_b64_tr_b16 v[222:223], v173 offset:19744
	ds_read_b64_tr_b16 v[224:225], v173 offset:20832
	s_waitcnt lgkmcnt(10)
	v_mfma_f32_16x16x32_bf16 v[158:161], v[226:229], v[38:41], v[158:161]
	v_mfma_f32_16x16x32_bf16 v[94:97], v[226:229], v[34:37], v[94:97]
	ds_read_b64_tr_b16 v[226:227], v173 offset:19776
	ds_read_b64_tr_b16 v[228:229], v173 offset:20864
	s_waitcnt lgkmcnt(10)
	v_mfma_f32_16x16x32_bf16 v[154:157], v[230:233], v[38:41], v[154:157]
	v_mfma_f32_16x16x32_bf16 v[90:93], v[230:233], v[34:37], v[90:93]
	ds_read_b64_tr_b16 v[230:231], v173 offset:19808
	ds_read_b64_tr_b16 v[232:233], v173 offset:20896
	s_waitcnt lgkmcnt(10)
	v_mfma_f32_16x16x32_bf16 v[150:153], v[236:239], v[38:41], v[150:153]
	v_mfma_f32_16x16x32_bf16 v[86:89], v[236:239], v[34:37], v[86:89]
	s_waitcnt lgkmcnt(8)
	v_mfma_f32_16x16x32_bf16 v[146:149], v[240:243], v[38:41], v[146:149]
	v_mfma_f32_16x16x32_bf16 v[82:85], v[240:243], v[34:37], v[82:85]
	s_waitcnt lgkmcnt(6)
	v_mfma_f32_16x16x32_bf16 v[142:145], v[218:221], v[38:41], v[142:145]
	v_mfma_f32_16x16x32_bf16 v[78:81], v[218:221], v[34:37], v[78:81]
	s_waitcnt lgkmcnt(4)
	v_mfma_f32_16x16x32_bf16 v[138:141], v[222:225], v[38:41], v[138:141]
	v_mfma_f32_16x16x32_bf16 v[74:77], v[222:225], v[34:37], v[74:77]
	s_waitcnt lgkmcnt(2)
	v_mfma_f32_16x16x32_bf16 v[134:137], v[226:229], v[38:41], v[134:137]
	v_mfma_f32_16x16x32_bf16 v[70:73], v[226:229], v[34:37], v[70:73]
	s_waitcnt lgkmcnt(0)
	v_mfma_f32_16x16x32_bf16 v[114:117], v[230:233], v[38:41], v[114:117]
	v_mfma_f32_16x16x32_bf16 v[66:69], v[230:233], v[34:37], v[66:69]
	s_and_saveexec_b64 s[20:21], s[22:23]
	s_cbranch_execz .LBB0_678
	v_readlane_b32 s22, v234, 45
	s_or_b64 s[18:19], s[18:19], exec
	s_nop 0
	v_mov_b32_e32 v1, s22
	ds_write_b32 v1, v200 offset:34848
